# v91 + EpiMid part 2 H stores widened to 16 bytes per lane with v_permlane16_swap (64-byte row segments, half the store instructions)
# speedup vs baseline: 1.0375x; 1.0065x over previous
; DI unsigned pk2(float lo, float hi) { unsigned r; asm("v_cvt_pk_bf16_f32 %0, %1, %2" : "=v"(r) : "v"(lo), "v"(hi)); return r; }
;     DI void operator()(f32x4 (&acc)[2][2][4][2], const pg8::Unit& u, int wr, int wc, int fr, int fq) const {
;     ...
;         asm volatile("s_waitcnt vmcnt(0) lgkmcnt(0)" ::: "memory"); __builtin_amdgcn_s_barrier(); asm volatile("" ::: "memory");
; #pragma unroll
;         for (int ai = 0; ai < 2; ++ai)
; #pragma unroll
;             for (int m = 0; m < 4; ++m) { const int rl = ai * 128 + wr * 64 + m * 16 + fr; const float rs = X[1024 + rl]; const size_t row = (size_t)u.pm * 256 + rl;
;                 const float* md = mod1 + (row >> 12) * 3072;
; #pragma unroll
;                 for (int bj = 0; bj < 2; ++bj)
; #pragma unroll
;                     for (int n = 0; n < 2; ++n) { const int col = col0 + bj * 128 + n * 16;
;                         const f32x4 gv = *(const f32x4*)(gno + col), sh = *(const f32x4*)(md + col), sc = *(const f32x4*)(md + 1024 + col);
;                         const f32x4 hv = acc[ai][bj][m][n] * rs * gv * (sc + 1.0f) + sh;
;                         u32x2 w; w.x = pk2(hv.x, hv.y); w.y = pk2(hv.z, hv.w); *(u32x2*)(H + row * DM + col) = w; }
;                 asm volatile("" ::: "memory"); }
.LBB0_808:
	s_or_b64 exec, exec, s[62:63]
	v_lshlrev_b64 v[172:173], 8, v[168:169]
	v_lshl_add_u64 v[176:177], v[172:173], 0, v[134:135]
	v_alignbit_b32 v166, v177, v176, 12
	v_mov_b64_e32 v[174:175], s[12:13]
	v_mad_u64_u32 v[170:171], s[10:11], v166, s94, v[174:175]
	v_lshrrev_b32_e32 v166, 12, v177
	v_mad_u32_u24 v171, v166, s94, v171
	v_lshl_add_u64 v[206:207], v[170:171], 0, s[48:49]
	v_lshlrev_b64 v[168:169], 2, v[158:159]
	s_waitcnt vmcnt(0) lgkmcnt(0)
	s_barrier
	v_lshl_add_u64 v[166:167], s[36:37], 0, v[168:169]
	v_lshl_add_u64 v[198:199], v[206:207], 0, v[168:169]
	v_lshl_add_u64 v[208:209], v[170:171], 0, v[168:169]
	global_load_dwordx4 v[130:133], v[166:167], off
	global_load_dwordx4 v[228:231], v[198:199], off
	global_load_dwordx4 v[178:181], v[208:209], off
	global_load_dwordx4 v[134:137], v[166:167], off offset:64
	global_load_dwordx4 v[232:235], v[198:199], off offset:64
	global_load_dwordx4 v[182:185], v[208:209], off offset:64
	global_load_dwordx4 v[138:141], v[166:167], off offset:512
	global_load_dwordx4 v[236:239], v[198:199], off offset:512
	global_load_dwordx4 v[186:189], v[208:209], off offset:512
	global_load_dwordx4 v[142:145], v[166:167], off offset:576
	global_load_dwordx4 v[240:243], v[198:199], off offset:576
	global_load_dwordx4 v[190:193], v[208:209], off offset:576
	v_and_b32_e32 v248, 15, v226
	v_lshrrev_b32_e32 v249, 8, v226
	v_lshl_or_b32 v248, v249, 6, v248
	v_lshl_add_u32 v248, v248, 2, s89
	ds_read_b32 v210, v248 offset:4096
	ds_read_b32 v212, v248 offset:4160
	ds_read_b32 v214, v248 offset:4224
	ds_read_b32 v216, v248 offset:4288
	ds_read_b32 v218, v248 offset:4608
	ds_read_b32 v220, v248 offset:4672
	ds_read_b32 v222, v248 offset:4736
	ds_read_b32 v224, v248 offset:4800
	v_lshlrev_b64 v[170:171], 1, v[158:159]
	v_lshlrev_b64 v[160:161], 11, v[176:177]
	v_lshl_add_u64 v[160:161], s[38:39], 0, v[160:161]
	v_lshl_add_u64 v[176:177], v[160:161], 0, v[170:171]
	v_bfe_u32 v156, v226, 4, 1
	v_mul_u32_u24_e32 v156, 24, v156
	v_mov_b32_e32 v157, 0
	v_lshl_add_u64 v[176:177], v[176:177], 0, v[156:157]
	s_mov_b32 s10, 0x8000
	s_mov_b32 s11, 0
	s_waitcnt vmcnt(0) lgkmcnt(0)
	v_pk_add_f32 v[228:229], v[228:229], 1.0 op_sel_hi:[1,0]
	v_pk_add_f32 v[230:231], v[230:231], 1.0 op_sel_hi:[1,0]
	v_pk_add_f32 v[232:233], v[232:233], 1.0 op_sel_hi:[1,0]
	v_pk_add_f32 v[234:235], v[234:235], 1.0 op_sel_hi:[1,0]
	v_pk_add_f32 v[236:237], v[236:237], 1.0 op_sel_hi:[1,0]
	v_pk_add_f32 v[238:239], v[238:239], 1.0 op_sel_hi:[1,0]
	v_pk_add_f32 v[240:241], v[240:241], 1.0 op_sel_hi:[1,0]
	v_pk_add_f32 v[242:243], v[242:243], 1.0 op_sel_hi:[1,0]
	v_pk_mul_f32 v[164:165], v[164:165], v[210:211] op_sel_hi:[1,0]
	v_pk_mul_f32 v[162:163], v[162:163], v[210:211] op_sel_hi:[1,0]
	v_pk_mul_f32 v[164:165], v[130:131], v[164:165]
	v_pk_mul_f32 v[162:163], v[132:133], v[162:163]
	v_pk_fma_f32 v[164:165], v[228:229], v[164:165], v[178:179]
	v_pk_fma_f32 v[162:163], v[230:231], v[162:163], v[180:181]
	v_cvt_pk_bf16_f32 v148, v164, v165
	v_cvt_pk_bf16_f32 v149, v162, v163
	v_pk_mul_f32 v[126:127], v[126:127], v[210:211] op_sel_hi:[1,0]
	v_pk_mul_f32 v[122:123], v[122:123], v[210:211] op_sel_hi:[1,0]
	v_pk_mul_f32 v[126:127], v[134:135], v[126:127]
	v_pk_mul_f32 v[122:123], v[136:137], v[122:123]
	v_pk_fma_f32 v[126:127], v[232:233], v[126:127], v[182:183]
	v_pk_fma_f32 v[122:123], v[234:235], v[122:123], v[184:185]
	v_cvt_pk_bf16_f32 v150, v126, v127
	v_cvt_pk_bf16_f32 v151, v122, v123
	s_nop 1
	v_permlane16_swap_b32_e32 v148, v150
	v_permlane16_swap_b32_e32 v149, v151
	global_store_dwordx4 v[176:177], v[148:151], off
	v_pk_mul_f32 v[116:117], v[116:117], v[210:211] op_sel_hi:[1,0]
	v_pk_mul_f32 v[118:119], v[118:119], v[210:211] op_sel_hi:[1,0]
	v_pk_mul_f32 v[116:117], v[138:139], v[116:117]
	v_pk_mul_f32 v[118:119], v[140:141], v[118:119]
	v_pk_fma_f32 v[116:117], v[236:237], v[116:117], v[186:187]
	v_pk_fma_f32 v[118:119], v[238:239], v[118:119], v[188:189]
	v_cvt_pk_bf16_f32 v152, v116, v117
	v_cvt_pk_bf16_f32 v153, v118, v119
	v_pk_mul_f32 v[112:113], v[112:113], v[210:211] op_sel_hi:[1,0]
	v_pk_mul_f32 v[114:115], v[114:115], v[210:211] op_sel_hi:[1,0]
	v_pk_mul_f32 v[112:113], v[142:143], v[112:113]
	v_pk_mul_f32 v[114:115], v[144:145], v[114:115]
	v_pk_fma_f32 v[112:113], v[240:241], v[112:113], v[190:191]
	v_pk_fma_f32 v[114:115], v[242:243], v[114:115], v[192:193]
	v_cvt_pk_bf16_f32 v154, v112, v113
	v_cvt_pk_bf16_f32 v155, v114, v115
	s_nop 1
	v_permlane16_swap_b32_e32 v152, v154
	v_permlane16_swap_b32_e32 v153, v155
	global_store_dwordx4 v[176:177], v[152:155], off offset:256
	v_lshl_add_u64 v[176:177], v[176:177], 0, s[10:11]
	v_pk_mul_f32 v[108:109], v[108:109], v[212:213] op_sel_hi:[1,0]
	v_pk_mul_f32 v[110:111], v[110:111], v[212:213] op_sel_hi:[1,0]
	v_pk_mul_f32 v[108:109], v[130:131], v[108:109]
	v_pk_mul_f32 v[110:111], v[132:133], v[110:111]
	v_pk_fma_f32 v[108:109], v[228:229], v[108:109], v[178:179]
	v_pk_fma_f32 v[110:111], v[230:231], v[110:111], v[180:181]
	v_cvt_pk_bf16_f32 v148, v108, v109
	v_cvt_pk_bf16_f32 v149, v110, v111
	v_pk_mul_f32 v[104:105], v[104:105], v[212:213] op_sel_hi:[1,0]
	v_pk_mul_f32 v[106:107], v[106:107], v[212:213] op_sel_hi:[1,0]
	v_pk_mul_f32 v[104:105], v[134:135], v[104:105]
	v_pk_mul_f32 v[106:107], v[136:137], v[106:107]
	v_pk_fma_f32 v[104:105], v[232:233], v[104:105], v[182:183]
	v_pk_fma_f32 v[106:107], v[234:235], v[106:107], v[184:185]
	v_cvt_pk_bf16_f32 v150, v104, v105
	v_cvt_pk_bf16_f32 v151, v106, v107
	s_nop 1
	v_permlane16_swap_b32_e32 v148, v150
	v_permlane16_swap_b32_e32 v149, v151
	global_store_dwordx4 v[176:177], v[148:151], off
	v_pk_mul_f32 v[100:101], v[100:101], v[212:213] op_sel_hi:[1,0]
; DI unsigned pk2(float lo, float hi) { unsigned r; asm("v_cvt_pk_bf16_f32 %0, %1, %2" : "=v"(r) : "v"(lo), "v"(hi)); return r; }
;     DI void operator()(f32x4 (&acc)[2][2][4][2], const pg8::Unit& u, int wr, int wc, int fr, int fq) const {
;     ...
; #pragma unroll
;         for (int ai = 0; ai < 2; ++ai)
; #pragma unroll
;             for (int m = 0; m < 4; ++m) { const int rl = ai * 128 + wr * 64 + m * 16 + fr; const float rs = X[1024 + rl]; const size_t row = (size_t)u.pm * 256 + rl;
;                 const float* md = mod1 + (row >> 12) * 3072;
; #pragma unroll
;                 for (int bj = 0; bj < 2; ++bj)
; #pragma unroll
;                     for (int n = 0; n < 2; ++n) { const int col = col0 + bj * 128 + n * 16;
;                         const f32x4 gv = *(const f32x4*)(gno + col), sh = *(const f32x4*)(md + col), sc = *(const f32x4*)(md + 1024 + col);
;                         const f32x4 hv = acc[ai][bj][m][n] * rs * gv * (sc + 1.0f) + sh;
;                         u32x2 w; w.x = pk2(hv.x, hv.y); w.y = pk2(hv.z, hv.w); *(u32x2*)(H + row * DM + col) = w; }
;                 asm volatile("" ::: "memory"); }
	v_pk_mul_f32 v[102:103], v[102:103], v[212:213] op_sel_hi:[1,0]
	v_pk_mul_f32 v[100:101], v[138:139], v[100:101]
	v_pk_mul_f32 v[102:103], v[140:141], v[102:103]
	v_pk_fma_f32 v[100:101], v[236:237], v[100:101], v[186:187]
	v_pk_fma_f32 v[102:103], v[238:239], v[102:103], v[188:189]
	v_cvt_pk_bf16_f32 v152, v100, v101
	v_cvt_pk_bf16_f32 v153, v102, v103
	v_pk_mul_f32 v[96:97], v[96:97], v[212:213] op_sel_hi:[1,0]
	v_pk_mul_f32 v[98:99], v[98:99], v[212:213] op_sel_hi:[1,0]
	v_pk_mul_f32 v[96:97], v[142:143], v[96:97]
	v_pk_mul_f32 v[98:99], v[144:145], v[98:99]
	v_pk_fma_f32 v[96:97], v[240:241], v[96:97], v[190:191]
	v_pk_fma_f32 v[98:99], v[242:243], v[98:99], v[192:193]
	v_cvt_pk_bf16_f32 v154, v96, v97
	v_cvt_pk_bf16_f32 v155, v98, v99
	s_nop 1
	v_permlane16_swap_b32_e32 v152, v154
	v_permlane16_swap_b32_e32 v153, v155
	global_store_dwordx4 v[176:177], v[152:155], off offset:256
	v_lshl_add_u64 v[176:177], v[176:177], 0, s[10:11]
	v_pk_mul_f32 v[92:93], v[92:93], v[214:215] op_sel_hi:[1,0]
	v_pk_mul_f32 v[94:95], v[94:95], v[214:215] op_sel_hi:[1,0]
	v_pk_mul_f32 v[92:93], v[130:131], v[92:93]
	v_pk_mul_f32 v[94:95], v[132:133], v[94:95]
	v_pk_fma_f32 v[92:93], v[228:229], v[92:93], v[178:179]
	v_pk_fma_f32 v[94:95], v[230:231], v[94:95], v[180:181]
	v_cvt_pk_bf16_f32 v148, v92, v93
	v_cvt_pk_bf16_f32 v149, v94, v95
	v_pk_mul_f32 v[88:89], v[88:89], v[214:215] op_sel_hi:[1,0]
	v_pk_mul_f32 v[90:91], v[90:91], v[214:215] op_sel_hi:[1,0]
	v_pk_mul_f32 v[88:89], v[134:135], v[88:89]
	v_pk_mul_f32 v[90:91], v[136:137], v[90:91]
	v_pk_fma_f32 v[88:89], v[232:233], v[88:89], v[182:183]
	v_pk_fma_f32 v[90:91], v[234:235], v[90:91], v[184:185]
	v_cvt_pk_bf16_f32 v150, v88, v89
	v_cvt_pk_bf16_f32 v151, v90, v91
	s_nop 1
	v_permlane16_swap_b32_e32 v148, v150
	v_permlane16_swap_b32_e32 v149, v151
	global_store_dwordx4 v[176:177], v[148:151], off
	v_pk_mul_f32 v[84:85], v[84:85], v[214:215] op_sel_hi:[1,0]
	v_pk_mul_f32 v[86:87], v[86:87], v[214:215] op_sel_hi:[1,0]
	v_pk_mul_f32 v[84:85], v[138:139], v[84:85]
	v_pk_mul_f32 v[86:87], v[140:141], v[86:87]
	v_pk_fma_f32 v[84:85], v[236:237], v[84:85], v[186:187]
	v_pk_fma_f32 v[86:87], v[238:239], v[86:87], v[188:189]
	v_cvt_pk_bf16_f32 v152, v84, v85
	v_cvt_pk_bf16_f32 v153, v86, v87
	v_pk_mul_f32 v[80:81], v[80:81], v[214:215] op_sel_hi:[1,0]
	v_pk_mul_f32 v[82:83], v[82:83], v[214:215] op_sel_hi:[1,0]
	v_pk_mul_f32 v[80:81], v[142:143], v[80:81]
	v_pk_mul_f32 v[82:83], v[144:145], v[82:83]
	v_pk_fma_f32 v[80:81], v[240:241], v[80:81], v[190:191]
	v_pk_fma_f32 v[82:83], v[242:243], v[82:83], v[192:193]
	v_cvt_pk_bf16_f32 v154, v80, v81
	v_cvt_pk_bf16_f32 v155, v82, v83
	s_nop 1
	v_permlane16_swap_b32_e32 v152, v154
	v_permlane16_swap_b32_e32 v153, v155
	global_store_dwordx4 v[176:177], v[152:155], off offset:256
	v_lshl_add_u64 v[176:177], v[176:177], 0, s[10:11]
	v_pk_mul_f32 v[76:77], v[76:77], v[216:217] op_sel_hi:[1,0]
	v_pk_mul_f32 v[78:79], v[78:79], v[216:217] op_sel_hi:[1,0]
	v_pk_mul_f32 v[76:77], v[130:131], v[76:77]
	v_pk_mul_f32 v[78:79], v[132:133], v[78:79]
	v_pk_fma_f32 v[76:77], v[228:229], v[76:77], v[178:179]
	v_pk_fma_f32 v[78:79], v[230:231], v[78:79], v[180:181]
	v_cvt_pk_bf16_f32 v148, v76, v77
	v_cvt_pk_bf16_f32 v149, v78, v79
	v_pk_mul_f32 v[72:73], v[72:73], v[216:217] op_sel_hi:[1,0]
	v_pk_mul_f32 v[74:75], v[74:75], v[216:217] op_sel_hi:[1,0]
	v_pk_mul_f32 v[72:73], v[134:135], v[72:73]
	v_pk_mul_f32 v[74:75], v[136:137], v[74:75]
	v_pk_fma_f32 v[72:73], v[232:233], v[72:73], v[182:183]
	v_pk_fma_f32 v[74:75], v[234:235], v[74:75], v[184:185]
	v_cvt_pk_bf16_f32 v150, v72, v73
	v_cvt_pk_bf16_f32 v151, v74, v75
	s_nop 1
	v_permlane16_swap_b32_e32 v148, v150
	v_permlane16_swap_b32_e32 v149, v151
	global_store_dwordx4 v[176:177], v[148:151], off
	v_pk_mul_f32 v[68:69], v[68:69], v[216:217] op_sel_hi:[1,0]
	v_pk_mul_f32 v[70:71], v[70:71], v[216:217] op_sel_hi:[1,0]
	v_pk_mul_f32 v[68:69], v[138:139], v[68:69]
	v_pk_mul_f32 v[70:71], v[140:141], v[70:71]
	v_pk_fma_f32 v[68:69], v[236:237], v[68:69], v[186:187]
	v_pk_fma_f32 v[70:71], v[238:239], v[70:71], v[188:189]
	v_cvt_pk_bf16_f32 v152, v68, v69
	v_cvt_pk_bf16_f32 v153, v70, v71
	v_pk_mul_f32 v[64:65], v[64:65], v[216:217] op_sel_hi:[1,0]
	v_pk_mul_f32 v[66:67], v[66:67], v[216:217] op_sel_hi:[1,0]
	v_pk_mul_f32 v[64:65], v[142:143], v[64:65]
	v_pk_mul_f32 v[66:67], v[144:145], v[66:67]
	v_pk_fma_f32 v[64:65], v[240:241], v[64:65], v[190:191]
	v_pk_fma_f32 v[66:67], v[242:243], v[66:67], v[192:193]
	v_cvt_pk_bf16_f32 v154, v64, v65
	v_cvt_pk_bf16_f32 v155, v66, v67
	s_nop 1
	v_permlane16_swap_b32_e32 v152, v154
	v_permlane16_swap_b32_e32 v153, v155
	global_store_dwordx4 v[176:177], v[152:155], off offset:256
	s_mov_b32 s10, 0x28000
	v_lshl_add_u64 v[176:177], v[176:177], 0, s[10:11]
	s_mov_b32 s10, 0x8000
	v_pk_mul_f32 v[60:61], v[60:61], v[218:219] op_sel_hi:[1,0]
	v_pk_mul_f32 v[62:63], v[62:63], v[218:219] op_sel_hi:[1,0]
	v_pk_mul_f32 v[60:61], v[130:131], v[60:61]
	v_pk_mul_f32 v[62:63], v[132:133], v[62:63]
	v_pk_fma_f32 v[60:61], v[228:229], v[60:61], v[178:179]
	v_pk_fma_f32 v[62:63], v[230:231], v[62:63], v[180:181]
	v_cvt_pk_bf16_f32 v148, v60, v61
	v_cvt_pk_bf16_f32 v149, v62, v63
	v_pk_mul_f32 v[56:57], v[56:57], v[218:219] op_sel_hi:[1,0]
	v_pk_mul_f32 v[58:59], v[58:59], v[218:219] op_sel_hi:[1,0]
	v_pk_mul_f32 v[56:57], v[134:135], v[56:57]
	v_pk_mul_f32 v[58:59], v[136:137], v[58:59]
	v_pk_fma_f32 v[56:57], v[232:233], v[56:57], v[182:183]
	v_pk_fma_f32 v[58:59], v[234:235], v[58:59], v[184:185]
	v_cvt_pk_bf16_f32 v150, v56, v57
	v_cvt_pk_bf16_f32 v151, v58, v59
	s_nop 1
	v_permlane16_swap_b32_e32 v148, v150
; DI unsigned pk2(float lo, float hi) { unsigned r; asm("v_cvt_pk_bf16_f32 %0, %1, %2" : "=v"(r) : "v"(lo), "v"(hi)); return r; }
;     DI void operator()(f32x4 (&acc)[2][2][4][2], const pg8::Unit& u, int wr, int wc, int fr, int fq) const {
;     ...
; #pragma unroll
;         for (int ai = 0; ai < 2; ++ai)
; #pragma unroll
;             for (int m = 0; m < 4; ++m) { const int rl = ai * 128 + wr * 64 + m * 16 + fr; const float rs = X[1024 + rl]; const size_t row = (size_t)u.pm * 256 + rl;
;                 const float* md = mod1 + (row >> 12) * 3072;
; #pragma unroll
;                 for (int bj = 0; bj < 2; ++bj)
; #pragma unroll
;                     for (int n = 0; n < 2; ++n) { const int col = col0 + bj * 128 + n * 16;
;                         const f32x4 gv = *(const f32x4*)(gno + col), sh = *(const f32x4*)(md + col), sc = *(const f32x4*)(md + 1024 + col);
;                         const f32x4 hv = acc[ai][bj][m][n] * rs * gv * (sc + 1.0f) + sh;
;                         u32x2 w; w.x = pk2(hv.x, hv.y); w.y = pk2(hv.z, hv.w); *(u32x2*)(H + row * DM + col) = w; }
;                 asm volatile("" ::: "memory"); }
;         asm volatile("s_waitcnt lgkmcnt(0)" ::: "memory"); __builtin_amdgcn_s_barrier(); asm volatile("" ::: "memory");
	v_permlane16_swap_b32_e32 v149, v151
	global_store_dwordx4 v[176:177], v[148:151], off
	v_pk_mul_f32 v[52:53], v[52:53], v[218:219] op_sel_hi:[1,0]
	v_pk_mul_f32 v[54:55], v[54:55], v[218:219] op_sel_hi:[1,0]
	v_pk_mul_f32 v[52:53], v[138:139], v[52:53]
	v_pk_mul_f32 v[54:55], v[140:141], v[54:55]
	v_pk_fma_f32 v[52:53], v[236:237], v[52:53], v[186:187]
	v_pk_fma_f32 v[54:55], v[238:239], v[54:55], v[188:189]
	v_cvt_pk_bf16_f32 v152, v52, v53
	v_cvt_pk_bf16_f32 v153, v54, v55
	v_pk_mul_f32 v[48:49], v[48:49], v[218:219] op_sel_hi:[1,0]
	v_pk_mul_f32 v[50:51], v[50:51], v[218:219] op_sel_hi:[1,0]
	v_pk_mul_f32 v[48:49], v[142:143], v[48:49]
	v_pk_mul_f32 v[50:51], v[144:145], v[50:51]
	v_pk_fma_f32 v[48:49], v[240:241], v[48:49], v[190:191]
	v_pk_fma_f32 v[50:51], v[242:243], v[50:51], v[192:193]
	v_cvt_pk_bf16_f32 v154, v48, v49
	v_cvt_pk_bf16_f32 v155, v50, v51
	s_nop 1
	v_permlane16_swap_b32_e32 v152, v154
	v_permlane16_swap_b32_e32 v153, v155
	global_store_dwordx4 v[176:177], v[152:155], off offset:256
	v_lshl_add_u64 v[176:177], v[176:177], 0, s[10:11]
	v_pk_mul_f32 v[44:45], v[44:45], v[220:221] op_sel_hi:[1,0]
	v_pk_mul_f32 v[46:47], v[46:47], v[220:221] op_sel_hi:[1,0]
	v_pk_mul_f32 v[44:45], v[130:131], v[44:45]
	v_pk_mul_f32 v[46:47], v[132:133], v[46:47]
	v_pk_fma_f32 v[44:45], v[228:229], v[44:45], v[178:179]
	v_pk_fma_f32 v[46:47], v[230:231], v[46:47], v[180:181]
	v_cvt_pk_bf16_f32 v148, v44, v45
	v_cvt_pk_bf16_f32 v149, v46, v47
	v_pk_mul_f32 v[40:41], v[40:41], v[220:221] op_sel_hi:[1,0]
	v_pk_mul_f32 v[42:43], v[42:43], v[220:221] op_sel_hi:[1,0]
	v_pk_mul_f32 v[40:41], v[134:135], v[40:41]
	v_pk_mul_f32 v[42:43], v[136:137], v[42:43]
	v_pk_fma_f32 v[40:41], v[232:233], v[40:41], v[182:183]
	v_pk_fma_f32 v[42:43], v[234:235], v[42:43], v[184:185]
	v_cvt_pk_bf16_f32 v150, v40, v41
	v_cvt_pk_bf16_f32 v151, v42, v43
	s_nop 1
	v_permlane16_swap_b32_e32 v148, v150
	v_permlane16_swap_b32_e32 v149, v151
	global_store_dwordx4 v[176:177], v[148:151], off
	v_pk_mul_f32 v[36:37], v[36:37], v[220:221] op_sel_hi:[1,0]
	v_pk_mul_f32 v[38:39], v[38:39], v[220:221] op_sel_hi:[1,0]
	v_pk_mul_f32 v[36:37], v[138:139], v[36:37]
	v_pk_mul_f32 v[38:39], v[140:141], v[38:39]
	v_pk_fma_f32 v[36:37], v[236:237], v[36:37], v[186:187]
	v_pk_fma_f32 v[38:39], v[238:239], v[38:39], v[188:189]
	v_cvt_pk_bf16_f32 v152, v36, v37
	v_cvt_pk_bf16_f32 v153, v38, v39
	v_pk_mul_f32 v[32:33], v[32:33], v[220:221] op_sel_hi:[1,0]
	v_pk_mul_f32 v[34:35], v[34:35], v[220:221] op_sel_hi:[1,0]
	v_pk_mul_f32 v[32:33], v[142:143], v[32:33]
	v_pk_mul_f32 v[34:35], v[144:145], v[34:35]
	v_pk_fma_f32 v[32:33], v[240:241], v[32:33], v[190:191]
	v_pk_fma_f32 v[34:35], v[242:243], v[34:35], v[192:193]
	v_cvt_pk_bf16_f32 v154, v32, v33
	v_cvt_pk_bf16_f32 v155, v34, v35
	s_nop 1
	v_permlane16_swap_b32_e32 v152, v154
	v_permlane16_swap_b32_e32 v153, v155
	global_store_dwordx4 v[176:177], v[152:155], off offset:256
	v_lshl_add_u64 v[176:177], v[176:177], 0, s[10:11]
	v_pk_mul_f32 v[28:29], v[28:29], v[222:223] op_sel_hi:[1,0]
	v_pk_mul_f32 v[30:31], v[30:31], v[222:223] op_sel_hi:[1,0]
	v_pk_mul_f32 v[28:29], v[130:131], v[28:29]
	v_pk_mul_f32 v[30:31], v[132:133], v[30:31]
	v_pk_fma_f32 v[28:29], v[228:229], v[28:29], v[178:179]
	v_pk_fma_f32 v[30:31], v[230:231], v[30:31], v[180:181]
	v_cvt_pk_bf16_f32 v148, v28, v29
	v_cvt_pk_bf16_f32 v149, v30, v31
	v_pk_mul_f32 v[24:25], v[24:25], v[222:223] op_sel_hi:[1,0]
	v_pk_mul_f32 v[26:27], v[26:27], v[222:223] op_sel_hi:[1,0]
	v_pk_mul_f32 v[24:25], v[134:135], v[24:25]
	v_pk_mul_f32 v[26:27], v[136:137], v[26:27]
	v_pk_fma_f32 v[24:25], v[232:233], v[24:25], v[182:183]
	v_pk_fma_f32 v[26:27], v[234:235], v[26:27], v[184:185]
	v_cvt_pk_bf16_f32 v150, v24, v25
	v_cvt_pk_bf16_f32 v151, v26, v27
	s_nop 1
	v_permlane16_swap_b32_e32 v148, v150
	v_permlane16_swap_b32_e32 v149, v151
	global_store_dwordx4 v[176:177], v[148:151], off
	v_pk_mul_f32 v[20:21], v[20:21], v[222:223] op_sel_hi:[1,0]
	v_pk_mul_f32 v[22:23], v[22:23], v[222:223] op_sel_hi:[1,0]
	v_pk_mul_f32 v[20:21], v[138:139], v[20:21]
	v_pk_mul_f32 v[22:23], v[140:141], v[22:23]
	v_pk_fma_f32 v[20:21], v[236:237], v[20:21], v[186:187]
	v_pk_fma_f32 v[22:23], v[238:239], v[22:23], v[188:189]
	v_cvt_pk_bf16_f32 v152, v20, v21
	v_cvt_pk_bf16_f32 v153, v22, v23
	v_pk_mul_f32 v[16:17], v[16:17], v[222:223] op_sel_hi:[1,0]
	v_pk_mul_f32 v[18:19], v[18:19], v[222:223] op_sel_hi:[1,0]
	v_pk_mul_f32 v[16:17], v[142:143], v[16:17]
	v_pk_mul_f32 v[18:19], v[144:145], v[18:19]
	v_pk_fma_f32 v[16:17], v[240:241], v[16:17], v[190:191]
	v_pk_fma_f32 v[18:19], v[242:243], v[18:19], v[192:193]
	v_cvt_pk_bf16_f32 v154, v16, v17
	v_cvt_pk_bf16_f32 v155, v18, v19
	s_nop 1
	v_permlane16_swap_b32_e32 v152, v154
	v_permlane16_swap_b32_e32 v153, v155
	global_store_dwordx4 v[176:177], v[152:155], off offset:256
	v_lshl_add_u64 v[176:177], v[176:177], 0, s[10:11]
	v_pk_mul_f32 v[12:13], v[12:13], v[224:225] op_sel_hi:[1,0]
	v_pk_mul_f32 v[14:15], v[14:15], v[224:225] op_sel_hi:[1,0]
	v_pk_mul_f32 v[12:13], v[130:131], v[12:13]
	v_pk_mul_f32 v[14:15], v[132:133], v[14:15]
	v_pk_fma_f32 v[12:13], v[228:229], v[12:13], v[178:179]
	v_pk_fma_f32 v[14:15], v[230:231], v[14:15], v[180:181]
	v_cvt_pk_bf16_f32 v148, v12, v13
	v_cvt_pk_bf16_f32 v149, v14, v15
	v_pk_mul_f32 v[8:9], v[8:9], v[224:225] op_sel_hi:[1,0]
	v_pk_mul_f32 v[10:11], v[10:11], v[224:225] op_sel_hi:[1,0]
	v_pk_mul_f32 v[8:9], v[134:135], v[8:9]
	v_pk_mul_f32 v[10:11], v[136:137], v[10:11]
	v_pk_fma_f32 v[8:9], v[232:233], v[8:9], v[182:183]
	v_pk_fma_f32 v[10:11], v[234:235], v[10:11], v[184:185]
	v_cvt_pk_bf16_f32 v150, v8, v9
	v_cvt_pk_bf16_f32 v151, v10, v11
	s_nop 1
	v_permlane16_swap_b32_e32 v148, v150
	v_permlane16_swap_b32_e32 v149, v151
	global_store_dwordx4 v[176:177], v[148:151], off
	v_pk_mul_f32 v[4:5], v[4:5], v[224:225] op_sel_hi:[1,0]
	v_pk_mul_f32 v[6:7], v[6:7], v[224:225] op_sel_hi:[1,0]
	v_pk_mul_f32 v[4:5], v[138:139], v[4:5]
	v_pk_mul_f32 v[6:7], v[140:141], v[6:7]
	v_pk_fma_f32 v[4:5], v[236:237], v[4:5], v[186:187]
	v_pk_fma_f32 v[6:7], v[238:239], v[6:7], v[188:189]
	v_cvt_pk_bf16_f32 v152, v4, v5
	v_cvt_pk_bf16_f32 v153, v6, v7
	v_pk_mul_f32 v[0:1], v[0:1], v[224:225] op_sel_hi:[1,0]
	v_pk_mul_f32 v[2:3], v[2:3], v[224:225] op_sel_hi:[1,0]
	v_pk_mul_f32 v[0:1], v[142:143], v[0:1]
	v_pk_mul_f32 v[2:3], v[144:145], v[2:3]
	v_pk_fma_f32 v[0:1], v[240:241], v[0:1], v[190:191]
	v_pk_fma_f32 v[2:3], v[242:243], v[2:3], v[192:193]
	v_cvt_pk_bf16_f32 v154, v0, v1
	v_cvt_pk_bf16_f32 v155, v2, v3
	s_nop 1
	v_permlane16_swap_b32_e32 v152, v154
	v_permlane16_swap_b32_e32 v153, v155
	global_store_dwordx4 v[176:177], v[152:155], off offset:256
	s_andn2_b64 vcc, exec, s[8:9]
	s_mov_b64 s[8:9], -1
	s_waitcnt lgkmcnt(0)
	s_barrier
	s_cbranch_vccnz .LBB0_765
	s_andn2_b64 vcc, exec, s[16:17]
	s_cbranch_vccnz .LBB0_764
	s_barrier
	s_branch .LBB0_764
